# mixer C: mask-bit extracts fill the wait states behind the last QK MFMA (replacing s_nop padding)
# baseline (speedup 1.0000x reference)
; DI float fexp2(float x) { return __builtin_amdgcn_exp2f(x); }
; DI f32x16 mfma32(bf16x8 a, bf16x8 b, f32x16 c) { return __builtin_amdgcn_mfma_f32_32x32x16_bf16(a, b, c, 0, 0, 0); }
; DI void lds_fence() { asm volatile("s_waitcnt lgkmcnt(0)" ::: "memory"); __builtin_amdgcn_wave_barrier(); }
; DI float half_max(float v) { auto rr = __builtin_amdgcn_permlane32_swap(__float_as_uint(v), __float_as_uint(v), false, false); return fmaxf(__uint_as_float(rr[0]), __uint_as_float(rr[1])); }
; template <int DVB, bool MASKED = true>
; DI void attn_step32(const bf16* Kt, int KP, const bf16* Vt, int VP, const bf16x8 (&qf)[4], f32x16 (&o)[DVB], float& m, float& l, unsigned vmask, float c2, int lane) {
;     ...
;   for (int t = 0; t < 4; ++t) { const bf16x8 kf = *(const bf16x8*)(Kt + r32 * KP + t * 16 + h * 8); s = mfma32(kf, qf[t], s); }
;   float mx = -INFINITY;
; #pragma unroll
;   for (int i = 0; i < 16; ++i) { if (MASKED) { s[i] = ((vmask >> i) & 1u) ? s[i] : -INFINITY; } mx = fmaxf(mx, s[i]); }
;   mx = half_max(mx);
;   const float mxs = mx * c2;
;   if (__any(mxs > m + 6.f)) {
;     const float mn = fmaxf(m, mxs);
;     const float alpha = fexp2(m - mn); l *= alpha;
; #pragma unroll
;     for (int d = 0; d < DVB; ++d)
; #pragma unroll
;       for (int i = 0; i < 16; ++i) o[d][i] *= alpha;
;     m = mn;
;   }
; template <int DVB>
; DI void band_run(const bf16* Kg, const bf16* Vg, int NP, int kbase, int nsteps, int dil, int roff, int qidx, int win,
;                  const bf16x8 (&qf)[4], f32x16 (&o)[DVB], float& m, float& l, float c2, bf16* Ks, bf16* Vs, int lane) {
;     ...
;   for (int j = 0; j < nsteps; ++j) {
;     lds_fence();
;     kv_store(R, Ks, Vs, lane);
;     lds_fence();
;     if (j + 1 < nsteps) band_load(R, Kg, Vg, NP, kbase + 32 * (j + 1), dil, roff, lane);
;     const int kb = kbase + 32 * j, lo_r = (qidx - win > 0 ? qidx - win : 0) - kb;
;     const unsigned vm = lane_rows(row_range_mask(lo_r, qidx - kb), h);
;     attn_step32<DVB>(Ks, WP, Vs, WP, qf, o, m, l, vm, c2, lane);
.LBB0_2620:
	v_max_i32_e32 v0, 0, v132
	v_lshl_or_b32 v0, v0, 4, v125
	v_lshlrev_b64 v[34:35], 13, v[0:1]
	s_waitcnt lgkmcnt(0)
	s_waitcnt vmcnt(7)
	ds_write_b128 v113, v[66:69]
	s_waitcnt vmcnt(6)
	ds_write_b128 v113, v[70:73] offset:4608
	s_waitcnt vmcnt(5)
	ds_write_b128 v113, v[74:77] offset:1152
	s_waitcnt vmcnt(4)
	ds_write_b128 v113, v[78:81] offset:5760
	s_waitcnt vmcnt(3)
	ds_write_b128 v113, v[82:85] offset:2304
	s_waitcnt vmcnt(2)
	ds_write_b128 v113, v[86:89] offset:6912
	s_waitcnt vmcnt(1)
	ds_write_b128 v113, v[94:97] offset:3456
	s_waitcnt vmcnt(0)
	ds_write_b128 v113, v[90:93] offset:8064
	v_or_b32_e32 v34, v34, v122
	s_waitcnt lgkmcnt(0)
	v_lshl_add_u64 v[38:39], v[110:111], 0, v[34:35]
	ds_read_b128 v[34:37], v114
	ds_read_b128 v[200:203], v114 offset:32
	ds_read_b128 v[204:207], v114 offset:64
	ds_read_b128 v[208:211], v114 offset:96
	v_max_i32_e32 v0, -8, v132
	v_lshl_add_u32 v0, v0, 4, v133
	global_load_dwordx4 v[66:69], v[38:39], off offset:1024
	global_load_dwordx4 v[70:73], v[38:39], off offset:2048
	v_lshlrev_b64 v[38:39], 13, v[0:1]
	v_or_b32_e32 v38, v38, v122
	v_lshl_add_u64 v[86:87], v[110:111], 0, v[38:39]
	s_waitcnt lgkmcnt(3)
	v_mfma_f32_32x32x16_bf16 v[34:49], v[34:37], v[62:65], 0
	global_load_dwordx4 v[74:77], v[86:87], off offset:1024
	global_load_dwordx4 v[78:81], v[86:87], off offset:2048
	v_max_i32_e32 v0, -16, v132
	v_lshl_add_u32 v0, v0, 4, v134
	v_lshlrev_b64 v[86:87], 13, v[0:1]
	v_max_i32_e32 v0, 0xffffffe8, v132
	v_lshl_add_u32 v0, v0, 4, v135
	s_waitcnt lgkmcnt(2)
	v_mfma_f32_32x32x16_bf16 v[34:49], v[200:203], v[58:61], v[34:49]
	v_lshlrev_b64 v[94:95], 13, v[0:1]
	v_or_b32_e32 v86, v86, v122
	v_or_b32_e32 v94, v94, v122
	v_lshl_add_u64 v[86:87], v[110:111], 0, v[86:87]
	v_lshl_add_u64 v[140:141], v[110:111], 0, v[94:95]
	global_load_dwordx4 v[82:85], v[86:87], off offset:1024
	s_nop 0
	global_load_dwordx4 v[86:89], v[86:87], off offset:2048
	s_waitcnt lgkmcnt(1)
	v_mfma_f32_32x32x16_bf16 v[34:49], v[204:207], v[54:57], v[34:49]
	global_load_dwordx4 v[94:97], v[140:141], off offset:1024
	global_load_dwordx4 v[90:93], v[140:141], off offset:2048
	v_add_u32_e32 v0, s15, v129
	v_max_i32_e32 v140, 0, v0
	v_lshlrev_b32_e64 v140, v140, -1
	v_cmp_gt_i32_e32 vcc, 32, v0
	s_waitcnt lgkmcnt(0)
	v_mfma_f32_32x32x16_bf16 v[34:49], v[208:211], v[50:53], v[34:49]
	v_cndmask_b32_e32 v0, 0, v140, vcc
	v_lshrrev_b32_e32 v140, v98, v0
	v_bfe_i32 v156, v140, 0, 1
	v_bfe_i32 v157, v140, 1, 1
	v_bfe_i32 v158, v140, 2, 1
	v_bfe_i32 v159, v140, 3, 1
	v_bfe_i32 v160, v140, 8, 1
	v_bfe_i32 v161, v140, 9, 1
	v_bfe_i32 v162, v140, 10, 1
	v_bfe_i32 v163, v140, 11, 1
	v_bfe_i32 v164, v140, 16, 1
	v_bfe_i32 v165, v140, 17, 1
	v_bfe_i32 v166, v140, 18, 1
	v_bfe_i32 v167, v140, 19, 1
	v_bfe_i32 v168, v140, 24, 1
	v_bfe_i32 v169, v140, 25, 1
	v_bfe_i32 v170, v140, 26, 1
	v_bfe_i32 v171, v140, 27, 1
	v_bfi_b32 v34, v156, v34, v123
	v_bfi_b32 v35, v157, v35, v123
	v_max3_f32 v137, v34, s2, v35
	v_bfi_b32 v136, v158, v36, v123
	v_bfi_b32 v0, v159, v37, v123
	v_max3_f32 v137, v137, v136, v0
	v_bfi_b32 v36, v160, v38, v123
	v_bfi_b32 v37, v161, v39, v123
	v_max3_f32 v137, v137, v36, v37
	v_bfi_b32 v38, v162, v40, v123
	v_bfi_b32 v39, v163, v41, v123
	v_max3_f32 v137, v137, v38, v39
	v_bfi_b32 v40, v164, v42, v123
	v_bfi_b32 v41, v165, v43, v123
	v_max3_f32 v137, v137, v40, v41
	v_bfi_b32 v42, v166, v44, v123
	v_bfi_b32 v43, v167, v45, v123
	v_max3_f32 v137, v137, v42, v43
	v_bfi_b32 v44, v168, v46, v123
	v_bfi_b32 v45, v169, v47, v123
	v_max3_f32 v137, v137, v44, v45
	v_bfi_b32 v46, v170, v48, v123
	s_nop 1
	v_bfi_b32 v47, v171, v49, v123
	v_max3_f32 v48, v137, v46, v47
	v_mov_b32_e32 v49, v48
	s_nop 1
	v_permlane32_swap_b32_e32 v48, v49
	v_max_f32_e32 v49, v49, v49
	v_max_f32_e32 v48, v48, v48
	v_max_f32_e32 v48, v48, v49
	v_mul_f32_e32 v48, 0x3e38aa3b, v48
	v_add_f32_e32 v49, 0x40c00000, v124
	v_cmp_gt_f32_e32 vcc, v48, v49
	s_cbranch_vccz .LBB0_2619
	v_max_f32_e32 v48, v48, v48
	v_max_f32_e32 v49, v124, v124
	v_max_f32_e32 v49, v49, v48
	v_sub_f32_e32 v48, v124, v49
	v_exp_f32_e32 v48, v48
	v_mov_b32_e32 v124, v49
	v_mul_f32_e32 v130, v130, v48
	v_pk_mul_f32 v[32:33], v[32:33], v[48:49] op_sel_hi:[1,0]
	v_pk_mul_f32 v[30:31], v[30:31], v[48:49] op_sel_hi:[1,0]
	v_pk_mul_f32 v[28:29], v[28:29], v[48:49] op_sel_hi:[1,0]
	v_pk_mul_f32 v[26:27], v[26:27], v[48:49] op_sel_hi:[1,0]
	v_pk_mul_f32 v[24:25], v[24:25], v[48:49] op_sel_hi:[1,0]
	v_pk_mul_f32 v[22:23], v[22:23], v[48:49] op_sel_hi:[1,0]
	v_pk_mul_f32 v[20:21], v[20:21], v[48:49] op_sel_hi:[1,0]
	v_pk_mul_f32 v[18:19], v[18:19], v[48:49] op_sel_hi:[1,0]
	v_pk_mul_f32 v[16:17], v[16:17], v[48:49] op_sel_hi:[1,0]
	v_pk_mul_f32 v[14:15], v[14:15], v[48:49] op_sel_hi:[1,0]
	v_pk_mul_f32 v[12:13], v[12:13], v[48:49] op_sel_hi:[1,0]
	v_pk_mul_f32 v[10:11], v[10:11], v[48:49] op_sel_hi:[1,0]
	v_pk_mul_f32 v[8:9], v[8:9], v[48:49] op_sel_hi:[1,0]
	v_pk_mul_f32 v[6:7], v[6:7], v[48:49] op_sel_hi:[1,0]
	v_pk_mul_f32 v[4:5], v[4:5], v[48:49] op_sel_hi:[1,0]
	v_pk_mul_f32 v[2:3], v[2:3], v[48:49] op_sel_hi:[1,0]
	s_branch .LBB0_2619

; DI float fexp2(float x) { return __builtin_amdgcn_exp2f(x); }
; DI f32x16 mfma32(bf16x8 a, bf16x8 b, f32x16 c) { return __builtin_amdgcn_mfma_f32_32x32x16_bf16(a, b, c, 0, 0, 0); }
; DI void lds_fence() { asm volatile("s_waitcnt lgkmcnt(0)" ::: "memory"); __builtin_amdgcn_wave_barrier(); }
; DI float half_max(float v) { auto rr = __builtin_amdgcn_permlane32_swap(__float_as_uint(v), __float_as_uint(v), false, false); return fmaxf(__uint_as_float(rr[0]), __uint_as_float(rr[1])); }
; template <int DVB, bool MASKED = true>
; DI void attn_step32(const bf16* Kt, int KP, const bf16* Vt, int VP, const bf16x8 (&qf)[4], f32x16 (&o)[DVB], float& m, float& l, unsigned vmask, float c2, int lane) {
;     ...
;   for (int t = 0; t < 4; ++t) { const bf16x8 kf = *(const bf16x8*)(Kt + r32 * KP + t * 16 + h * 8); s = mfma32(kf, qf[t], s); }
;   float mx = -INFINITY;
; #pragma unroll
;   for (int i = 0; i < 16; ++i) { if (MASKED) { s[i] = ((vmask >> i) & 1u) ? s[i] : -INFINITY; } mx = fmaxf(mx, s[i]); }
;   mx = half_max(mx);
;   const float mxs = mx * c2;
;   if (__any(mxs > m + 6.f)) {
;     const float mn = fmaxf(m, mxs);
;     const float alpha = fexp2(m - mn); l *= alpha;
; #pragma unroll
;     for (int d = 0; d < DVB; ++d)
; #pragma unroll
;       for (int i = 0; i < 16; ++i) o[d][i] *= alpha;
;     m = mn;
;   }
; template <int DVB>
; DI void band_run(const bf16* Kg, const bf16* Vg, int NP, int kbase, int nsteps, int dil, int roff, int qidx, int win,
;                  const bf16x8 (&qf)[4], f32x16 (&o)[DVB], float& m, float& l, float c2, bf16* Ks, bf16* Vs, int lane) {
;     ...
;   for (int j = 0; j < nsteps; ++j) {
;     lds_fence();
;     kv_store(R, Ks, Vs, lane);
;     lds_fence();
;     if (j + 1 < nsteps) band_load(R, Kg, Vg, NP, kbase + 32 * (j + 1), dil, roff, lane);
;     const int kb = kbase + 32 * j, lo_r = (qidx - win > 0 ? qidx - win : 0) - kb;
;     const unsigned vm = lane_rows(row_range_mask(lo_r, qidx - kb), h);
;     attn_step32<DVB>(Ks, WP, Vs, WP, qf, o, m, l, vm, c2, lane);
.LBB0_2628:
	v_max_i32_e32 v0, 0, v135
	v_lshl_or_b32 v0, v0, 2, v133
	v_lshlrev_b64 v[34:35], 13, v[0:1]
	v_or_b32_e32 v34, v34, v122
	v_max_i32_e32 v0, -8, v135
	s_waitcnt lgkmcnt(0)
	s_waitcnt vmcnt(7)
	ds_write_b128 v113, v[66:69]
	s_waitcnt vmcnt(6)
	ds_write_b128 v113, v[70:73] offset:4608
	s_waitcnt vmcnt(5)
	ds_write_b128 v113, v[74:77] offset:1152
	s_waitcnt vmcnt(4)
	ds_write_b128 v113, v[78:81] offset:5760
	s_waitcnt vmcnt(3)
	ds_write_b128 v113, v[82:85] offset:2304
	s_waitcnt vmcnt(2)
	ds_write_b128 v113, v[86:89] offset:6912
	s_waitcnt vmcnt(1)
	ds_write_b128 v113, v[94:97] offset:3456
	s_waitcnt vmcnt(0)
	ds_write_b128 v113, v[90:93] offset:8064
	v_lshl_add_u64 v[34:35], v[110:111], 0, v[34:35]
	v_lshl_add_u32 v0, v0, 2, v136
	s_waitcnt lgkmcnt(0)
	global_load_dwordx4 v[66:69], v[34:35], off offset:1024
	global_load_dwordx4 v[70:73], v[34:35], off offset:2048
	v_lshlrev_b64 v[34:35], 13, v[0:1]
	v_max_i32_e32 v0, -16, v135
	v_lshl_add_u32 v0, v0, 2, v137
	v_lshlrev_b64 v[38:39], 13, v[0:1]
	v_max_i32_e32 v0, 0xffffffe8, v135
	v_lshl_add_u32 v0, v0, 2, v138
	v_lshlrev_b64 v[90:91], 13, v[0:1]
	v_or_b32_e32 v34, v34, v122
	v_or_b32_e32 v38, v38, v122
	v_or_b32_e32 v90, v90, v122
	v_lshl_add_u64 v[34:35], v[110:111], 0, v[34:35]
	v_lshl_add_u64 v[38:39], v[110:111], 0, v[38:39]
	v_lshl_add_u64 v[90:91], v[110:111], 0, v[90:91]
	global_load_dwordx4 v[74:77], v[34:35], off offset:1024
	global_load_dwordx4 v[78:81], v[34:35], off offset:2048
	ds_read_b128 v[34:37], v114
	ds_read_b128 v[200:203], v114 offset:32
	ds_read_b128 v[204:207], v114 offset:64
	ds_read_b128 v[208:211], v114 offset:96
	global_load_dwordx4 v[82:85], v[38:39], off offset:1024
	global_load_dwordx4 v[86:89], v[38:39], off offset:2048
	global_load_dwordx4 v[94:97], v[90:91], off offset:1024
	s_nop 0
	global_load_dwordx4 v[90:93], v[90:91], off offset:2048
	s_waitcnt lgkmcnt(3)
	v_mfma_f32_32x32x16_bf16 v[34:49], v[34:37], v[62:65], 0
	v_add_u32_e32 v139, s15, v119
	v_min_i32_e32 v148, 31, v139
	v_add_u32_e32 v0, s15, v134
	v_max_i32_e32 v0, 0, v0
	v_cmp_gt_i32_e32 vcc, 31, v139
	s_waitcnt lgkmcnt(2)
	v_mfma_f32_32x32x16_bf16 v[34:49], v[200:203], v[58:61], v[34:49]
	v_add_u32_e32 v140, 1, v148
	v_lshlrev_b32_e64 v140, v140, -1
	v_not_b32_e32 v149, v140
	v_cndmask_b32_e32 v139, -1, v149, vcc
	v_cmp_ge_i32_e32 vcc, v148, v0
	s_waitcnt lgkmcnt(1)
	v_mfma_f32_32x32x16_bf16 v[34:49], v[204:207], v[54:57], v[34:49]
	v_lshlrev_b32_e64 v144, v0, -1
	v_and_b32_e32 v139, v139, v144
	v_cndmask_b32_e32 v0, 0, v139, vcc
	v_lshrrev_b32_e32 v144, v98, v0
	s_nop 0
	s_nop 0
	s_nop 0
	s_waitcnt lgkmcnt(0)
	v_mfma_f32_32x32x16_bf16 v[34:49], v[208:211], v[50:53], v[34:49]
	v_bfe_i32 v156, v144, 0, 1
	v_bfe_i32 v157, v144, 1, 1
	v_bfe_i32 v158, v144, 2, 1
	v_bfe_i32 v159, v144, 3, 1
	v_bfe_i32 v160, v144, 8, 1
	v_bfe_i32 v161, v144, 9, 1
	v_bfe_i32 v162, v144, 10, 1
	v_bfe_i32 v163, v144, 11, 1
	v_bfe_i32 v164, v144, 16, 1
	v_bfe_i32 v165, v144, 17, 1
	v_bfe_i32 v166, v144, 18, 1
	v_bfe_i32 v167, v144, 19, 1
	v_bfe_i32 v168, v144, 24, 1
	v_bfe_i32 v169, v144, 25, 1
	v_bfe_i32 v170, v144, 26, 1
	v_bfe_i32 v171, v144, 27, 1
	v_bfi_b32 v34, v156, v34, v123
	v_bfi_b32 v35, v157, v35, v123
	v_max3_f32 v140, v34, s2, v35
	v_bfi_b32 v139, v158, v36, v123
	v_bfi_b32 v0, v159, v37, v123
	v_max3_f32 v140, v140, v139, v0
	v_bfi_b32 v36, v160, v38, v123
	v_bfi_b32 v37, v161, v39, v123
	v_max3_f32 v140, v140, v36, v37
	v_bfi_b32 v38, v162, v40, v123
	v_bfi_b32 v39, v163, v41, v123
	v_max3_f32 v140, v140, v38, v39
	v_bfi_b32 v40, v164, v42, v123
	v_bfi_b32 v41, v165, v43, v123
	v_max3_f32 v140, v140, v40, v41
	v_bfi_b32 v42, v166, v44, v123
	v_bfi_b32 v43, v167, v45, v123
	v_max3_f32 v140, v140, v42, v43
	v_bfi_b32 v44, v168, v46, v123
	v_bfi_b32 v45, v169, v47, v123
	v_max3_f32 v140, v140, v44, v45
	v_bfi_b32 v46, v170, v48, v123
	s_nop 1
	v_bfi_b32 v47, v171, v49, v123
	v_max3_f32 v48, v140, v46, v47
	v_mov_b32_e32 v49, v48
	s_nop 1
	v_permlane32_swap_b32_e32 v48, v49
	v_max_f32_e32 v49, v49, v49
	v_max_f32_e32 v48, v48, v48
	v_max_f32_e32 v48, v48, v49
	v_mul_f32_e32 v48, 0x3e38aa3b, v48
	v_add_f32_e32 v49, 0x40c00000, v124
	v_cmp_gt_f32_e32 vcc, v48, v49
	s_cbranch_vccz .LBB0_2627
	v_max_f32_e32 v48, v48, v48
	v_max_f32_e32 v49, v124, v124
	v_max_f32_e32 v49, v49, v48
	v_sub_f32_e32 v48, v124, v49
	v_exp_f32_e32 v48, v48
	v_mov_b32_e32 v124, v49
	v_mul_f32_e32 v130, v130, v48
	v_pk_mul_f32 v[32:33], v[32:33], v[48:49] op_sel_hi:[1,0]
	v_pk_mul_f32 v[30:31], v[30:31], v[48:49] op_sel_hi:[1,0]
	v_pk_mul_f32 v[28:29], v[28:29], v[48:49] op_sel_hi:[1,0]
	v_pk_mul_f32 v[26:27], v[26:27], v[48:49] op_sel_hi:[1,0]
	v_pk_mul_f32 v[24:25], v[24:25], v[48:49] op_sel_hi:[1,0]
	v_pk_mul_f32 v[22:23], v[22:23], v[48:49] op_sel_hi:[1,0]
	v_pk_mul_f32 v[20:21], v[20:21], v[48:49] op_sel_hi:[1,0]
	v_pk_mul_f32 v[18:19], v[18:19], v[48:49] op_sel_hi:[1,0]
	v_pk_mul_f32 v[16:17], v[16:17], v[48:49] op_sel_hi:[1,0]
	v_pk_mul_f32 v[14:15], v[14:15], v[48:49] op_sel_hi:[1,0]
	v_pk_mul_f32 v[12:13], v[12:13], v[48:49] op_sel_hi:[1,0]
	v_pk_mul_f32 v[10:11], v[10:11], v[48:49] op_sel_hi:[1,0]
	v_pk_mul_f32 v[8:9], v[8:9], v[48:49] op_sel_hi:[1,0]
	v_pk_mul_f32 v[6:7], v[6:7], v[48:49] op_sel_hi:[1,0]
	v_pk_mul_f32 v[4:5], v[4:5], v[48:49] op_sel_hi:[1,0]
	v_pk_mul_f32 v[2:3], v[2:3], v[48:49] op_sel_hi:[1,0]
	s_branch .LBB0_2627

; DI float fexp2(float x) { return __builtin_amdgcn_exp2f(x); }
; DI f32x16 mfma32(bf16x8 a, bf16x8 b, f32x16 c) { return __builtin_amdgcn_mfma_f32_32x32x16_bf16(a, b, c, 0, 0, 0); }
; DI void lds_fence() { asm volatile("s_waitcnt lgkmcnt(0)" ::: "memory"); __builtin_amdgcn_wave_barrier(); }
; DI float half_max(float v) { auto rr = __builtin_amdgcn_permlane32_swap(__float_as_uint(v), __float_as_uint(v), false, false); return fmaxf(__uint_as_float(rr[0]), __uint_as_float(rr[1])); }
; template <int DVB, bool MASKED = true>
; DI void attn_step32(const bf16* Kt, int KP, const bf16* Vt, int VP, const bf16x8 (&qf)[4], f32x16 (&o)[DVB], float& m, float& l, unsigned vmask, float c2, int lane) {
;     ...
;   for (int t = 0; t < 4; ++t) { const bf16x8 kf = *(const bf16x8*)(Kt + r32 * KP + t * 16 + h * 8); s = mfma32(kf, qf[t], s); }
;   float mx = -INFINITY;
; #pragma unroll
;   for (int i = 0; i < 16; ++i) { if (MASKED) { s[i] = ((vmask >> i) & 1u) ? s[i] : -INFINITY; } mx = fmaxf(mx, s[i]); }
;   mx = half_max(mx);
;   const float mxs = mx * c2;
;   if (__any(mxs > m + 6.f)) {
;     const float mn = fmaxf(m, mxs);
;     const float alpha = fexp2(m - mn); l *= alpha;
; #pragma unroll
;     for (int d = 0; d < DVB; ++d)
; #pragma unroll
;       for (int i = 0; i < 16; ++i) o[d][i] *= alpha;
;     m = mn;
;   }
; template <int DVB>
; DI void band_run(const bf16* Kg, const bf16* Vg, int NP, int kbase, int nsteps, int dil, int roff, int qidx, int win,
;                  const bf16x8 (&qf)[4], f32x16 (&o)[DVB], float& m, float& l, float c2, bf16* Ks, bf16* Vs, int lane) {
;     ...
;   for (int j = 0; j < nsteps; ++j) {
;     lds_fence();
;     kv_store(R, Ks, Vs, lane);
;     lds_fence();
;     if (j + 1 < nsteps) band_load(R, Kg, Vg, NP, kbase + 32 * (j + 1), dil, roff, lane);
;     const int kb = kbase + 32 * j, lo_r = (qidx - win > 0 ? qidx - win : 0) - kb;
;     const unsigned vm = lane_rows(row_range_mask(lo_r, qidx - kb), h);
;     attn_step32<DVB>(Ks, WP, Vs, WP, qf, o, m, l, vm, c2, lane);
.LBB0_2635:
	v_max_i32_e32 v0, 0, v128
	v_lshlrev_b64 v[34:35], 13, v[0:1]
	v_or_b32_e32 v34, v34, v122
	v_max_i32_e32 v0, -8, v128
	s_waitcnt lgkmcnt(0)
	s_waitcnt vmcnt(7)
	ds_write_b128 v113, v[66:69]
	s_waitcnt vmcnt(6)
	ds_write_b128 v113, v[70:73] offset:4608
	s_waitcnt vmcnt(5)
	ds_write_b128 v113, v[74:77] offset:1152
	s_waitcnt vmcnt(4)
	ds_write_b128 v113, v[78:81] offset:5760
	s_waitcnt vmcnt(3)
	ds_write_b128 v113, v[82:85] offset:2304
	s_waitcnt vmcnt(2)
	ds_write_b128 v113, v[86:89] offset:6912
	s_waitcnt vmcnt(1)
	ds_write_b128 v113, v[94:97] offset:3456
	s_waitcnt vmcnt(0)
	ds_write_b128 v113, v[90:93] offset:8064
	v_lshl_add_u64 v[34:35], v[110:111], 0, v[34:35]
	v_add_u32_e32 v0, 8, v0
	s_waitcnt lgkmcnt(0)
	global_load_dwordx4 v[66:69], v[34:35], off offset:1024
	global_load_dwordx4 v[70:73], v[34:35], off offset:2048
	v_lshlrev_b64 v[34:35], 13, v[0:1]
	v_max_i32_e32 v0, -16, v128
	v_add_u32_e32 v0, 16, v0
	v_lshlrev_b64 v[38:39], 13, v[0:1]
	v_max_i32_e32 v0, 0xffffffe8, v128
	v_add_u32_e32 v0, 24, v0
	v_lshlrev_b64 v[90:91], 13, v[0:1]
	v_or_b32_e32 v34, v34, v122
	v_or_b32_e32 v38, v38, v122
	v_or_b32_e32 v90, v90, v122
	v_lshl_add_u64 v[34:35], v[110:111], 0, v[34:35]
	v_lshl_add_u64 v[38:39], v[110:111], 0, v[38:39]
	v_lshl_add_u64 v[90:91], v[110:111], 0, v[90:91]
	global_load_dwordx4 v[74:77], v[34:35], off offset:1024
	global_load_dwordx4 v[78:81], v[34:35], off offset:2048
	ds_read_b128 v[34:37], v114
	ds_read_b128 v[200:203], v114 offset:32
	ds_read_b128 v[204:207], v114 offset:64
	ds_read_b128 v[208:211], v114 offset:96
	global_load_dwordx4 v[82:85], v[38:39], off offset:1024
	global_load_dwordx4 v[86:89], v[38:39], off offset:2048
	global_load_dwordx4 v[94:97], v[90:91], off offset:1024
	s_nop 0
	global_load_dwordx4 v[90:93], v[90:91], off offset:2048
	s_waitcnt lgkmcnt(3)
	v_mfma_f32_32x32x16_bf16 v[34:49], v[34:37], v[62:65], 0
	v_add_u32_e32 v129, s15, v121
	v_min_i32_e32 v138, 31, v129
	v_add_u32_e32 v0, s15, v127
	v_max_i32_e32 v0, 0, v0
	v_cmp_gt_i32_e32 vcc, 31, v129
	s_waitcnt lgkmcnt(2)
	v_mfma_f32_32x32x16_bf16 v[34:49], v[200:203], v[58:61], v[34:49]
	v_add_u32_e32 v130, 1, v138
	v_lshlrev_b32_e64 v130, v130, -1
	v_not_b32_e32 v139, v130
	v_cndmask_b32_e32 v129, -1, v139, vcc
	v_cmp_ge_i32_e32 vcc, v138, v0
	s_waitcnt lgkmcnt(1)
	v_mfma_f32_32x32x16_bf16 v[34:49], v[204:207], v[54:57], v[34:49]
	v_lshlrev_b32_e64 v134, v0, -1
	v_and_b32_e32 v129, v129, v134
	v_cndmask_b32_e32 v0, 0, v129, vcc
	v_lshrrev_b32_e32 v134, v98, v0
	s_nop 0
	s_nop 0
	s_nop 0
	s_waitcnt lgkmcnt(0)
	v_mfma_f32_32x32x16_bf16 v[34:49], v[208:211], v[50:53], v[34:49]
	v_bfe_i32 v156, v134, 0, 1
	v_bfe_i32 v157, v134, 1, 1
	v_bfe_i32 v158, v134, 2, 1
	v_bfe_i32 v159, v134, 3, 1
	v_bfe_i32 v160, v134, 8, 1
	v_bfe_i32 v161, v134, 9, 1
	v_bfe_i32 v162, v134, 10, 1
	v_bfe_i32 v163, v134, 11, 1
	v_bfe_i32 v164, v134, 16, 1
	v_bfe_i32 v165, v134, 17, 1
	v_bfe_i32 v166, v134, 18, 1
	v_bfe_i32 v167, v134, 19, 1
	v_bfe_i32 v168, v134, 24, 1
	v_bfe_i32 v169, v134, 25, 1
	v_bfe_i32 v170, v134, 26, 1
	v_bfe_i32 v171, v134, 27, 1
	v_bfi_b32 v34, v156, v34, v123
	v_bfi_b32 v35, v157, v35, v123
	v_max3_f32 v130, v34, s2, v35
	v_bfi_b32 v129, v158, v36, v123
	v_bfi_b32 v0, v159, v37, v123
	v_max3_f32 v130, v130, v129, v0
	v_bfi_b32 v36, v160, v38, v123
	v_bfi_b32 v37, v161, v39, v123
	v_max3_f32 v130, v130, v36, v37
	v_bfi_b32 v38, v162, v40, v123
	v_bfi_b32 v39, v163, v41, v123
	v_max3_f32 v130, v130, v38, v39
	v_bfi_b32 v40, v164, v42, v123
	v_bfi_b32 v41, v165, v43, v123
	v_max3_f32 v130, v130, v40, v41
	v_bfi_b32 v42, v166, v44, v123
	v_bfi_b32 v43, v167, v45, v123
	v_max3_f32 v130, v130, v42, v43
	v_bfi_b32 v44, v168, v46, v123
	v_bfi_b32 v45, v169, v47, v123
	v_max3_f32 v130, v130, v44, v45
	v_bfi_b32 v46, v170, v48, v123
	s_nop 1
	v_bfi_b32 v47, v171, v49, v123
	v_max3_f32 v48, v130, v46, v47
	v_mov_b32_e32 v49, v48
	s_nop 1
	v_permlane32_swap_b32_e32 v48, v49
	v_max_f32_e32 v49, v49, v49
	v_max_f32_e32 v48, v48, v48
	v_max_f32_e32 v48, v48, v49
	v_mul_f32_e32 v48, 0x3e38aa3b, v48
	v_add_f32_e32 v49, 0x40c00000, v124
	v_cmp_gt_f32_e32 vcc, v48, v49
	s_cbranch_vccz .LBB0_2634
	v_max_f32_e32 v48, v48, v48
	v_max_f32_e32 v49, v124, v124
	v_max_f32_e32 v49, v49, v48
	v_sub_f32_e32 v48, v124, v49
	v_exp_f32_e32 v48, v48
	v_mov_b32_e32 v124, v49
	v_mul_f32_e32 v125, v125, v48
	v_pk_mul_f32 v[32:33], v[32:33], v[48:49] op_sel_hi:[1,0]
	v_pk_mul_f32 v[30:31], v[30:31], v[48:49] op_sel_hi:[1,0]
	v_pk_mul_f32 v[28:29], v[28:29], v[48:49] op_sel_hi:[1,0]
	v_pk_mul_f32 v[26:27], v[26:27], v[48:49] op_sel_hi:[1,0]
	v_pk_mul_f32 v[24:25], v[24:25], v[48:49] op_sel_hi:[1,0]
	v_pk_mul_f32 v[22:23], v[22:23], v[48:49] op_sel_hi:[1,0]
	v_pk_mul_f32 v[20:21], v[20:21], v[48:49] op_sel_hi:[1,0]
	v_pk_mul_f32 v[18:19], v[18:19], v[48:49] op_sel_hi:[1,0]
	v_pk_mul_f32 v[16:17], v[16:17], v[48:49] op_sel_hi:[1,0]
	v_pk_mul_f32 v[14:15], v[14:15], v[48:49] op_sel_hi:[1,0]
	v_pk_mul_f32 v[12:13], v[12:13], v[48:49] op_sel_hi:[1,0]
	v_pk_mul_f32 v[10:11], v[10:11], v[48:49] op_sel_hi:[1,0]
	v_pk_mul_f32 v[8:9], v[8:9], v[48:49] op_sel_hi:[1,0]
	v_pk_mul_f32 v[6:7], v[6:7], v[48:49] op_sel_hi:[1,0]
	v_pk_mul_f32 v[4:5], v[4:5], v[48:49] op_sel_hi:[1,0]
	v_pk_mul_f32 v[2:3], v[2:3], v[48:49] op_sel_hi:[1,0]
	s_branch .LBB0_2634
